# rs-table loads batched (16 loads then one wait) in 5 GEMM phase prologues; sb-attn output stores as dwordx4 via permlane32_swap; sb-in epilogue full-128B-line stores via column remap + DPP row exchang
# speedup vs baseline: 1.0079x; 1.0079x over previous
; #define GAS __attribute__((address_space(1)))
; __device__ __forceinline__ float rs_from_ssp(const GAS float* ssp, int row) {
;     const GAS f32x4* p = (const GAS f32x4*)(ssp + (size_t)row * 16);
;     const f32x4 a = p[0], b = p[1], c = p[2], d = p[3];
;     const f32x4 s = (a + b) + (c + d);
;     return __builtin_amdgcn_rsqf(((s.x + s.y) + (s.z + s.w)) * (1.f / 1024.f) + EPS);
; }
; template <class Epi>
; __device__ __forceinline__ void gemm_phase(LAS unsigned char* lds, const Gemm g, const StaticOrder& S, const Epi& E) {
;     ...
;     if constexpr (Epi::USES_RS) { if (E.rs_src()) {
;         const int hi = __builtin_amdgcn_readfirstlane(tid >> 8), rw = tid & 255;
;         Unit u0; (void)S.next(0, u0);
; #pragma unroll
;         for (int j = 0; j < 4; ++j) { Unit uu; const int pmj = S.next(2 * j + hi, uu) ? uu.pm : u0.pm;
;             rsl[(2 * j + hi) * 256 + rw] = rs_from_ssp(E.rs_src(), pmj * 256 + rw); } } }
.LBB0_209:
	v_and_b32_e32 v3, 0xff, v1
	v_lshl_or_b32 v4, s13, 8, v3
	v_ashrrev_i32_e32 v5, 31, v4
	v_lshlrev_b64 v[4:5], 6, v[4:5]
	v_lshl_add_u64 v[16:17], s[10:11], 0, v[4:5]
	global_load_dwordx4 v[44:47], v[16:17], off offset:32
	global_load_dwordx4 v[48:51], v[16:17], off offset:48
	global_load_dwordx4 v[52:55], v[16:17], off
	s_nop 0
	global_load_dwordx4 v[56:59], v[16:17], off offset:16
	s_add_i32 s19, s18, 2
	v_lshlrev_b32_e32 v2, 2, v3
	s_mul_i32 s12, s19, s77
	s_mul_hi_i32 s13, s19, s77
	s_add_u32 s12, s12, s75
	s_addc_u32 s13, s13, s17
	v_lshl_or_b32 v64, s18, 10, v2
	v_mov_b64_e32 v[4:5], 0xff
	v_cmp_gt_i64_e32 vcc, s[12:13], v[4:5]
	s_mov_b32 s13, s16
	s_cbranch_vccnz .LBB0_215
	s_ashr_i32 s13, s12, 31
	s_lshr_b32 s13, s13, 29
	s_add_i32 s21, s12, s13
	s_and_b32 s13, s21, -8
	s_sub_i32 s22, s12, s13
	s_cmp_lt_i32 s22, 0
	s_mov_b64 s[12:13], -1
	s_cbranch_scc1 .LBB0_212
	s_lshl_b32 s23, s22, 5
	s_mov_b64 s[12:13], 0

; #define GAS __attribute__((address_space(1)))
; __device__ __forceinline__ float rs_from_ssp(const GAS float* ssp, int row) {
;     const GAS f32x4* p = (const GAS f32x4*)(ssp + (size_t)row * 16);
;     const f32x4 a = p[0], b = p[1], c = p[2], d = p[3];
;     const f32x4 s = (a + b) + (c + d);
;     return __builtin_amdgcn_rsqf(((s.x + s.y) + (s.z + s.w)) * (1.f / 1024.f) + EPS);
; }
; template <class Epi>
; __device__ __forceinline__ void gemm_phase(LAS unsigned char* lds, const Gemm g, const StaticOrder& S, const Epi& E) {
;     ...
;     if constexpr (Epi::USES_RS) { if (E.rs_src()) {
;         const int hi = __builtin_amdgcn_readfirstlane(tid >> 8), rw = tid & 255;
;         Unit u0; (void)S.next(0, u0);
; #pragma unroll
;         for (int j = 0; j < 4; ++j) { Unit uu; const int pmj = S.next(2 * j + hi, uu) ? uu.pm : u0.pm;
;             rsl[(2 * j + hi) * 256 + rw] = rs_from_ssp(E.rs_src(), pmj * 256 + rw); } } }
.LBB0_215:
	v_lshl_or_b32 v4, s13, 8, v3
	v_ashrrev_i32_e32 v5, 31, v4
	v_lshlrev_b64 v[4:5], 6, v[4:5]
	v_lshl_add_u64 v[16:17], s[10:11], 0, v[4:5]
	global_load_dwordx4 v[84:87], v[16:17], off offset:32
	global_load_dwordx4 v[88:91], v[16:17], off offset:48
	global_load_dwordx4 v[92:95], v[16:17], off
	s_nop 0
	global_load_dwordx4 v[96:99], v[16:17], off offset:16
	v_lshl_or_b32 v104, s19, 10, v2
	s_add_i32 s19, s18, 4
	s_mul_i32 s12, s19, s77
	s_mul_hi_i32 s13, s19, s77
	s_add_u32 s12, s12, s75
	s_addc_u32 s13, s13, s17
	v_mov_b64_e32 v[4:5], 0xff
	v_cmp_gt_i64_e32 vcc, s[12:13], v[4:5]
	s_mov_b32 s13, s16
	s_cbranch_vccnz .LBB0_221
	s_ashr_i32 s13, s12, 31
	s_lshr_b32 s13, s13, 29
	s_add_i32 s21, s12, s13
	s_and_b32 s13, s21, -8
	s_sub_i32 s22, s12, s13
	s_cmp_lt_i32 s22, 0
	s_mov_b64 s[12:13], -1
	s_cbranch_scc1 .LBB0_218
	s_lshl_b32 s23, s22, 5
	s_mov_b64 s[12:13], 0

; #define GAS __attribute__((address_space(1)))
; __device__ __forceinline__ float rs_from_ssp(const GAS float* ssp, int row) {
;     const GAS f32x4* p = (const GAS f32x4*)(ssp + (size_t)row * 16);
;     const f32x4 a = p[0], b = p[1], c = p[2], d = p[3];
;     const f32x4 s = (a + b) + (c + d);
;     return __builtin_amdgcn_rsqf(((s.x + s.y) + (s.z + s.w)) * (1.f / 1024.f) + EPS);
; }
; template <class Epi>
; __device__ __forceinline__ void gemm_phase(LAS unsigned char* lds, const Gemm g, const StaticOrder& S, const Epi& E) {
;     ...
;     if constexpr (Epi::USES_RS) { if (E.rs_src()) {
;         const int hi = __builtin_amdgcn_readfirstlane(tid >> 8), rw = tid & 255;
;         Unit u0; (void)S.next(0, u0);
; #pragma unroll
;         for (int j = 0; j < 4; ++j) { Unit uu; const int pmj = S.next(2 * j + hi, uu) ? uu.pm : u0.pm;
;             rsl[(2 * j + hi) * 256 + rw] = rs_from_ssp(E.rs_src(), pmj * 256 + rw); } } }
.LBB0_221:
	v_lshl_or_b32 v4, s13, 8, v3
	v_ashrrev_i32_e32 v5, 31, v4
	v_lshlrev_b64 v[4:5], 6, v[4:5]
	v_lshl_add_u64 v[16:17], s[10:11], 0, v[4:5]
	global_load_dwordx4 v[124:127], v[16:17], off offset:32
	global_load_dwordx4 v[128:131], v[16:17], off offset:48
	global_load_dwordx4 v[132:135], v[16:17], off
	s_nop 0
	global_load_dwordx4 v[136:139], v[16:17], off offset:16
	s_add_i32 s18, s18, 6
	s_mul_i32 s12, s18, s77
	s_mul_hi_i32 s13, s18, s77
	s_add_u32 s12, s12, s75
	s_addc_u32 s13, s13, s17
	v_lshl_or_b32 v144, s19, 10, v2
	v_mov_b64_e32 v[4:5], 0xff
	v_cmp_gt_i64_e32 vcc, s[12:13], v[4:5]
	s_cbranch_vccnz .LBB0_227
	s_ashr_i32 s13, s12, 31
	s_lshr_b32 s13, s13, 29
	s_add_i32 s16, s12, s13
	s_and_b32 s13, s16, -8
	s_sub_i32 s17, s12, s13
	s_cmp_lt_i32 s17, 0
	s_mov_b64 s[12:13], -1
	s_cbranch_scc1 .LBB0_224
	s_lshl_b32 s19, s17, 5
	s_mov_b64 s[12:13], 0

; #define GAS __attribute__((address_space(1)))
; __device__ __forceinline__ float rs_from_ssp(const GAS float* ssp, int row) {
;     const GAS f32x4* p = (const GAS f32x4*)(ssp + (size_t)row * 16);
;     const f32x4 a = p[0], b = p[1], c = p[2], d = p[3];
;     const f32x4 s = (a + b) + (c + d);
;     return __builtin_amdgcn_rsqf(((s.x + s.y) + (s.z + s.w)) * (1.f / 1024.f) + EPS);
; }
; template <class Epi>
; __device__ __forceinline__ void gemm_phase(LAS unsigned char* lds, const Gemm g, const StaticOrder& S, const Epi& E) {
;     ...
;     if constexpr (Epi::USES_RS) { if (E.rs_src()) {
;         const int hi = __builtin_amdgcn_readfirstlane(tid >> 8), rw = tid & 255;
;         Unit u0; (void)S.next(0, u0);
; #pragma unroll
;         for (int j = 0; j < 4; ++j) { Unit uu; const int pmj = S.next(2 * j + hi, uu) ? uu.pm : u0.pm;
;             rsl[(2 * j + hi) * 256 + rw] = rs_from_ssp(E.rs_src(), pmj * 256 + rw); } } }
.LBB0_227:
	v_lshl_or_b32 v4, s16, 8, v3
	v_ashrrev_i32_e32 v5, 31, v4
	v_lshlrev_b64 v[4:5], 6, v[4:5]
	v_lshl_add_u64 v[16:17], s[10:11], 0, v[4:5]
	global_load_dwordx4 v[4:7], v[16:17], off
	global_load_dwordx4 v[8:11], v[16:17], off offset:16
	global_load_dwordx4 v[12:15], v[16:17], off offset:32
	s_nop 0
	global_load_dwordx4 v[16:19], v[16:17], off offset:48
	v_lshl_or_b32 v2, s18, 10, v2
	s_waitcnt vmcnt(4)
	v_pk_add_f32 v[46:47], v[46:47], v[50:51]
	v_pk_add_f32 v[44:45], v[44:45], v[48:49]
	v_pk_add_f32 v[54:55], v[54:55], v[58:59]
	v_pk_add_f32 v[52:53], v[52:53], v[56:57]
	v_pk_add_f32 v[46:47], v[54:55], v[46:47]
	v_pk_add_f32 v[44:45], v[52:53], v[44:45]
	s_nop 0
	v_pk_mov_b32 v[48:49], v[44:45], v[46:47] op_sel:[1,0]
	v_mov_b32_e32 v45, v47
	v_pk_add_f32 v[44:45], v[48:49], v[44:45]
	s_nop 0
	v_add_f32_e32 v44, v44, v45
	v_fmamk_f32 v44, v44, 0x3a800000, v244
	v_rsq_f32_e32 v44, v44
	s_nop 0
	ds_write_b32 v64, v44
	v_pk_add_f32 v[86:87], v[86:87], v[90:91]
	v_pk_add_f32 v[84:85], v[84:85], v[88:89]
	v_pk_add_f32 v[94:95], v[94:95], v[98:99]
	v_pk_add_f32 v[92:93], v[92:93], v[96:97]
	v_pk_add_f32 v[86:87], v[94:95], v[86:87]
	v_pk_add_f32 v[84:85], v[92:93], v[84:85]
	s_nop 0
	v_pk_mov_b32 v[88:89], v[84:85], v[86:87] op_sel:[1,0]
	v_mov_b32_e32 v85, v87
	v_pk_add_f32 v[84:85], v[88:89], v[84:85]
	s_nop 0
	v_add_f32_e32 v84, v84, v85
	v_fmamk_f32 v84, v84, 0x3a800000, v244
	v_rsq_f32_e32 v84, v84
	s_nop 0
	ds_write_b32 v104, v84
	v_pk_add_f32 v[126:127], v[126:127], v[130:131]
	v_pk_add_f32 v[124:125], v[124:125], v[128:129]
	v_pk_add_f32 v[134:135], v[134:135], v[138:139]
	v_pk_add_f32 v[132:133], v[132:133], v[136:137]
	v_pk_add_f32 v[126:127], v[134:135], v[126:127]
	v_pk_add_f32 v[124:125], v[132:133], v[124:125]
	s_nop 0
	v_pk_mov_b32 v[128:129], v[124:125], v[126:127] op_sel:[1,0]
	v_mov_b32_e32 v125, v127
	v_pk_add_f32 v[124:125], v[128:129], v[124:125]
	s_nop 0
	v_add_f32_e32 v124, v124, v125
	v_fmamk_f32 v124, v124, 0x3a800000, v244
	v_rsq_f32_e32 v124, v124
	s_nop 0
	ds_write_b32 v144, v124
	s_waitcnt vmcnt(2)
	v_pk_add_f32 v[6:7], v[6:7], v[10:11]
	v_pk_add_f32 v[4:5], v[4:5], v[8:9]
	s_waitcnt vmcnt(0)
	v_pk_add_f32 v[8:9], v[14:15], v[18:19]
	v_pk_add_f32 v[10:11], v[12:13], v[16:17]
	v_pk_add_f32 v[6:7], v[6:7], v[8:9]
	v_pk_add_f32 v[4:5], v[4:5], v[10:11]
	s_nop 0
	v_pk_mov_b32 v[8:9], v[4:5], v[6:7] op_sel:[1,0]
	v_mov_b32_e32 v5, v7
	v_pk_add_f32 v[4:5], v[8:9], v[4:5]
	s_nop 0
	v_add_f32_e32 v3, v4, v5
	v_fmamk_f32 v3, v3, 0x3a800000, v244
	v_rsq_f32_e32 v3, v3
	ds_write_b32 v2, v3

;     __host__ __device__ bool next(int i, Unit& u) const {
;         const long L = (long)i * G + c; if (L >= nwg) return false;
;         int wgid = (int)L; { const int q = nwg / NXCD, r = nwg % NXCD, xcd = wgid % NXCD, off = wgid / NXCD; wgid = (xcd < r ? xcd * (q + 1) : r * (q + 1) + (xcd - r) * q) + off; }
;         const int nig = WGM * nN, gid = wgid / nig, fm = gid * WGM, gsz = (nM - fm) < WGM ? (nM - fm) : WGM;
;         u.pm = fm + ((wgid % nig) % gsz); u.pn = (wgid % nig) / gsz; return true;
;     }
; template <class Epi>
; __device__ __forceinline__ void gemm_phase(LAS unsigned char* lds, const Gemm g, const StaticOrder& S, const Epi& E) {
;     ...
;     if constexpr (Epi::USES_RS) { if (E.rs_src()) {
;         const int hi = __builtin_amdgcn_readfirstlane(tid >> 8), rw = tid & 255;
;         Unit u0; (void)S.next(0, u0);
; #pragma unroll
;         for (int j = 0; j < 4; ++j) { Unit uu; const int pmj = S.next(2 * j + hi, uu) ? uu.pm : u0.pm;
;             rsl[(2 * j + hi) * 256 + rw] = rs_from_ssp(E.rs_src(), pmj * 256 + rw); } } }
.LBB0_277:
	v_and_b32_e32 v2, 0xff, v10
	v_lshl_or_b32 v4, s13, 8, v2
	v_ashrrev_i32_e32 v5, 31, v4
	v_lshlrev_b64 v[4:5], 6, v[4:5]
	v_lshl_add_u64 v[8:9], s[10:11], 0, v[4:5]
	global_load_dwordx4 v[44:47], v[8:9], off offset:32
	global_load_dwordx4 v[52:55], v[8:9], off offset:48
	global_load_dwordx4 v[56:59], v[8:9], off
	global_load_dwordx4 v[60:63], v[8:9], off offset:16
	s_add_i32 s17, s16, 2
	v_lshlrev_b32_e32 v1, 2, v2
	s_mul_i32 s12, s17, s77
	s_mul_hi_i32 s13, s17, s77
	s_add_u32 s12, s12, s75
	s_addc_u32 s13, s13, s15
	v_lshl_or_b32 v64, s16, 10, v1
	v_mov_b64_e32 v[4:5], 0x57f
	v_cmp_gt_i64_e32 vcc, s[12:13], v[4:5]
	s_mov_b32 s13, s14
	s_cbranch_vccnz .LBB0_279
	s_ashr_i32 s13, s12, 31
	s_lshr_b32 s13, s13, 29
	s_add_i32 s13, s12, s13
	s_ashr_i32 s18, s13, 3
	s_and_b32 s13, s13, -8
	s_sub_i32 s12, s12, s13
	s_cmp_lt_i32 s12, 0
	s_movk_i32 s13, 0xb1
	s_cselect_b32 s13, s13, 0xb0
	s_mul_i32 s12, s12, s13
	s_add_i32 s12, s12, s18
	s_mul_hi_i32 s13, s12, 0x2e8ba2e9
	s_lshr_b32 s18, s13, 31
	s_ashr_i32 s13, s13, 4
	s_add_i32 s13, s13, s18
	s_lshl_b32 s18, s13, 2
	s_sub_i32 s19, 64, s18
	s_min_i32 s19, s19, 4
	s_abs_i32 s19, s19
	v_cvt_f32_u32_e32 v3, s19
	s_sub_i32 s20, 0, s19
	s_mulk_i32 s13, 0x58
	s_sub_i32 s12, s12, s13
	v_rcp_iflag_f32_e32 v3, v3
	s_ashr_i32 s13, s12, 31
	s_abs_i32 s12, s12
	v_mul_f32_e32 v3, 0x4f7ffffe, v3
	v_cvt_u32_f32_e32 v3, v3
	s_nop 0
	v_readfirstlane_b32 s21, v3
	s_mul_i32 s20, s20, s21
	s_mul_hi_u32 s20, s21, s20
	s_add_i32 s21, s21, s20
	s_mul_hi_u32 s20, s12, s21
	s_mul_i32 s20, s20, s19
	s_sub_i32 s12, s12, s20
	s_sub_i32 s20, s12, s19
	s_cmp_ge_u32 s12, s19
	s_cselect_b32 s12, s20, s12
	s_sub_i32 s20, s12, s19
	s_cmp_ge_u32 s12, s19
	s_cselect_b32 s12, s20, s12
	s_xor_b32 s12, s12, s13
	s_sub_i32 s12, s12, s13
	s_add_i32 s13, s18, s12
.LBB0_279:
	v_lshl_or_b32 v4, s13, 8, v2
	v_ashrrev_i32_e32 v5, 31, v4
	v_lshlrev_b64 v[4:5], 6, v[4:5]
	v_lshl_add_u64 v[8:9], s[10:11], 0, v[4:5]
	global_load_dwordx4 v[84:87], v[8:9], off offset:32
	global_load_dwordx4 v[92:95], v[8:9], off offset:48
	global_load_dwordx4 v[96:99], v[8:9], off
	global_load_dwordx4 v[100:103], v[8:9], off offset:16
	v_lshl_or_b32 v104, s17, 10, v1
	s_add_i32 s17, s16, 4
	s_mul_i32 s12, s17, s77
	s_mul_hi_i32 s13, s17, s77
	s_add_u32 s12, s12, s75
	s_addc_u32 s13, s13, s15
	v_mov_b64_e32 v[4:5], 0x57f
	v_cmp_gt_i64_e32 vcc, s[12:13], v[4:5]
	s_mov_b32 s13, s14
	s_cbranch_vccnz .LBB0_281
	s_ashr_i32 s13, s12, 31
	s_lshr_b32 s13, s13, 29
	s_add_i32 s13, s12, s13
	s_ashr_i32 s18, s13, 3
	s_and_b32 s13, s13, -8
	s_sub_i32 s12, s12, s13
	s_cmp_lt_i32 s12, 0
	s_movk_i32 s13, 0xb1
	s_cselect_b32 s13, s13, 0xb0
	s_mul_i32 s12, s12, s13
	s_add_i32 s12, s12, s18
	s_mul_hi_i32 s13, s12, 0x2e8ba2e9
	s_lshr_b32 s18, s13, 31
	s_ashr_i32 s13, s13, 4
	s_add_i32 s13, s13, s18
	s_lshl_b32 s18, s13, 2
	s_sub_i32 s19, 64, s18
	s_min_i32 s19, s19, 4
	s_abs_i32 s19, s19
	v_cvt_f32_u32_e32 v3, s19
	s_sub_i32 s20, 0, s19
	s_mulk_i32 s13, 0x58
	s_sub_i32 s12, s12, s13
	v_rcp_iflag_f32_e32 v3, v3
	s_ashr_i32 s13, s12, 31
	s_abs_i32 s12, s12
	v_mul_f32_e32 v3, 0x4f7ffffe, v3
	v_cvt_u32_f32_e32 v3, v3
	s_nop 0
	v_readfirstlane_b32 s21, v3
	s_mul_i32 s20, s20, s21
	s_mul_hi_u32 s20, s21, s20
	s_add_i32 s21, s21, s20
	s_mul_hi_u32 s20, s12, s21
	s_mul_i32 s20, s20, s19
	s_sub_i32 s12, s12, s20
	s_sub_i32 s20, s12, s19
	s_cmp_ge_u32 s12, s19
	s_cselect_b32 s12, s20, s12
	s_sub_i32 s20, s12, s19
	s_cmp_ge_u32 s12, s19
	s_cselect_b32 s12, s20, s12
	s_xor_b32 s12, s12, s13
	s_sub_i32 s12, s12, s13
	s_add_i32 s13, s18, s12
;     __host__ __device__ bool next(int i, Unit& u) const {
;         const long L = (long)i * G + c; if (L >= nwg) return false;
;         int wgid = (int)L; { const int q = nwg / NXCD, r = nwg % NXCD, xcd = wgid % NXCD, off = wgid / NXCD; wgid = (xcd < r ? xcd * (q + 1) : r * (q + 1) + (xcd - r) * q) + off; }
;         const int nig = WGM * nN, gid = wgid / nig, fm = gid * WGM, gsz = (nM - fm) < WGM ? (nM - fm) : WGM;
;         u.pm = fm + ((wgid % nig) % gsz); u.pn = (wgid % nig) / gsz; return true;
;     }
; template <class Epi>
; __device__ __forceinline__ void gemm_phase(LAS unsigned char* lds, const Gemm g, const StaticOrder& S, const Epi& E) {
;     ...
;     if constexpr (Epi::USES_RS) { if (E.rs_src()) {
;         const int hi = __builtin_amdgcn_readfirstlane(tid >> 8), rw = tid & 255;
;         Unit u0; (void)S.next(0, u0);
; #pragma unroll
;         for (int j = 0; j < 4; ++j) { Unit uu; const int pmj = S.next(2 * j + hi, uu) ? uu.pm : u0.pm;
;             rsl[(2 * j + hi) * 256 + rw] = rs_from_ssp(E.rs_src(), pmj * 256 + rw); } } }
.LBB0_281:
	v_lshl_or_b32 v4, s13, 8, v2
	v_ashrrev_i32_e32 v5, 31, v4
	v_lshlrev_b64 v[4:5], 6, v[4:5]
	v_lshl_add_u64 v[8:9], s[10:11], 0, v[4:5]
	global_load_dwordx4 v[124:127], v[8:9], off offset:32
	global_load_dwordx4 v[132:135], v[8:9], off offset:48
	global_load_dwordx4 v[136:139], v[8:9], off
	global_load_dwordx4 v[140:143], v[8:9], off offset:16
	s_add_i32 s16, s16, 6
	s_mul_i32 s12, s16, s77
	s_mul_hi_i32 s13, s16, s77
	s_add_u32 s12, s12, s75
	s_addc_u32 s13, s13, s15
	v_lshl_or_b32 v144, s17, 10, v1
	v_mov_b64_e32 v[4:5], 0x57f
	v_cmp_gt_i64_e32 vcc, s[12:13], v[4:5]
	s_cbranch_vccnz .LBB0_283
	s_ashr_i32 s13, s12, 31
	s_lshr_b32 s13, s13, 29
	s_add_i32 s13, s12, s13
	s_ashr_i32 s14, s13, 3
	s_and_b32 s13, s13, -8
	s_sub_i32 s12, s12, s13
	s_cmp_lt_i32 s12, 0
	s_movk_i32 s13, 0xb1
	s_cselect_b32 s13, s13, 0xb0
	s_mul_i32 s12, s12, s13
	s_add_i32 s12, s12, s14
	s_mul_hi_i32 s13, s12, 0x2e8ba2e9
	s_lshr_b32 s14, s13, 31
	s_ashr_i32 s13, s13, 4
	s_add_i32 s13, s13, s14
	s_lshl_b32 s14, s13, 2
	s_sub_i32 s15, 64, s14
	s_min_i32 s15, s15, 4
	s_abs_i32 s15, s15
	v_cvt_f32_u32_e32 v3, s15
	s_sub_i32 s17, 0, s15
	s_mulk_i32 s13, 0x58
	s_sub_i32 s12, s12, s13
	v_rcp_iflag_f32_e32 v3, v3
	s_ashr_i32 s13, s12, 31
	s_abs_i32 s12, s12
	v_mul_f32_e32 v3, 0x4f7ffffe, v3
	v_cvt_u32_f32_e32 v3, v3
	s_nop 0
	v_readfirstlane_b32 s18, v3
	s_mul_i32 s17, s17, s18
	s_mul_hi_u32 s17, s18, s17
	s_add_i32 s18, s18, s17
	s_mul_hi_u32 s17, s12, s18
	s_mul_i32 s17, s17, s15
	s_sub_i32 s12, s12, s17
	s_sub_i32 s17, s12, s15
	s_cmp_ge_u32 s12, s15
	s_cselect_b32 s12, s17, s12
	s_sub_i32 s17, s12, s15
	s_cmp_ge_u32 s12, s15
	s_cselect_b32 s12, s17, s12
	s_xor_b32 s12, s12, s13
	s_sub_i32 s12, s12, s13
	s_add_i32 s14, s14, s12
.LBB0_283:
	v_lshl_or_b32 v2, s14, 8, v2
	v_ashrrev_i32_e32 v3, 31, v2
	v_lshlrev_b64 v[2:3], 6, v[2:3]
	v_lshl_add_u64 v[16:17], s[10:11], 0, v[2:3]
	global_load_dwordx4 v[2:5], v[16:17], off
	global_load_dwordx4 v[6:9], v[16:17], off offset:16
	global_load_dwordx4 v[12:15], v[16:17], off offset:32
	s_nop 0
	global_load_dwordx4 v[16:19], v[16:17], off offset:48
	v_lshl_or_b32 v1, s16, 10, v1
	s_waitcnt vmcnt(4)
	v_pk_add_f32 v[46:47], v[46:47], v[54:55]
	v_pk_add_f32 v[44:45], v[44:45], v[52:53]
	v_pk_add_f32 v[48:49], v[58:59], v[62:63]
	v_pk_add_f32 v[56:57], v[56:57], v[60:61]
	v_pk_add_f32 v[46:47], v[48:49], v[46:47]
	v_pk_add_f32 v[44:45], v[56:57], v[44:45]
	s_nop 0
	v_pk_mov_b32 v[48:49], v[44:45], v[46:47] op_sel:[1,0]
	v_mov_b32_e32 v45, v47
	v_pk_add_f32 v[44:45], v[48:49], v[44:45]
	s_nop 0
	v_add_f32_e32 v43, v44, v45
	v_fmamk_f32 v43, v43, 0x3a800000, v244
	v_rsq_f32_e32 v43, v43
	s_nop 0
	ds_write_b32 v64, v43
	v_pk_add_f32 v[86:87], v[86:87], v[94:95]
	v_pk_add_f32 v[84:85], v[84:85], v[92:93]
	v_pk_add_f32 v[88:89], v[98:99], v[102:103]
	v_pk_add_f32 v[96:97], v[96:97], v[100:101]
	v_pk_add_f32 v[86:87], v[88:89], v[86:87]
	v_pk_add_f32 v[84:85], v[96:97], v[84:85]
	s_nop 0
	v_pk_mov_b32 v[88:89], v[84:85], v[86:87] op_sel:[1,0]
	v_mov_b32_e32 v85, v87
	v_pk_add_f32 v[84:85], v[88:89], v[84:85]
	s_nop 0
	v_add_f32_e32 v83, v84, v85
	v_fmamk_f32 v83, v83, 0x3a800000, v244
	v_rsq_f32_e32 v83, v83
	s_nop 0
	ds_write_b32 v104, v83
	v_pk_add_f32 v[126:127], v[126:127], v[134:135]
	v_pk_add_f32 v[124:125], v[124:125], v[132:133]
	v_pk_add_f32 v[128:129], v[138:139], v[142:143]
	v_pk_add_f32 v[136:137], v[136:137], v[140:141]
	v_pk_add_f32 v[126:127], v[128:129], v[126:127]
	v_pk_add_f32 v[124:125], v[136:137], v[124:125]
	s_nop 0
	v_pk_mov_b32 v[128:129], v[124:125], v[126:127] op_sel:[1,0]
	v_mov_b32_e32 v125, v127
	v_pk_add_f32 v[124:125], v[128:129], v[124:125]
	s_nop 0
	v_add_f32_e32 v123, v124, v125
	v_fmamk_f32 v123, v123, 0x3a800000, v244
	v_rsq_f32_e32 v123, v123
	s_nop 0
	ds_write_b32 v144, v123
	s_waitcnt vmcnt(2)
	v_pk_add_f32 v[4:5], v[4:5], v[8:9]
	v_pk_add_f32 v[2:3], v[2:3], v[6:7]
	s_waitcnt vmcnt(0)
	v_pk_add_f32 v[6:7], v[14:15], v[18:19]
	v_pk_add_f32 v[8:9], v[12:13], v[16:17]
	v_pk_add_f32 v[4:5], v[4:5], v[6:7]
	v_pk_add_f32 v[2:3], v[2:3], v[8:9]
	s_nop 0
	v_pk_mov_b32 v[6:7], v[2:3], v[4:5] op_sel:[1,0]
	v_mov_b32_e32 v3, v5
	v_pk_add_f32 v[2:3], v[6:7], v[2:3]
	s_nop 0
	v_add_f32_e32 v2, v2, v3
	v_fmamk_f32 v2, v2, 0x3a800000, v244
	v_rsq_f32_e32 v2, v2
	ds_write_b32 v1, v2

; #define GAS __attribute__((address_space(1)))
; __device__ __forceinline__ unsigned cvt_pk_bf16(float lo, float hi) { unsigned r; asm volatile("v_cvt_pk_bf16_f32 %0, %1, %2" : "=v"(r) : "v"(lo), "v"(hi)); return r; }
; __device__ __forceinline__ void sb_attn_phase(const GAS bf16_t* qkv, GAS bf16_t* o, LAS unsigned char* lds, int G, int cblk) {
;     ...
;         GAS bf16_t* op = o + (seq0 + Q0 + r) * D + h * 64 + 4 * hh;
; #pragma unroll
;         for (int dvt = 0; dvt < 2; ++dvt)
; #pragma unroll
;             for (int i = 0; i < 4; ++i) {
;                 u32x2 wv; wv.x = cvt_pk_bf16(oacc[dvt][4 * i], oacc[dvt][4 * i + 1]); wv.y = cvt_pk_bf16(oacc[dvt][4 * i + 2], oacc[dvt][4 * i + 3]);
;                 *(GAS u32x2*)(op + 32 * dvt + 8 * i) = wv;
;             }
.LBB0_500:
	v_lshlrev_b64 v[34:35], 11, v[140:141]
	v_lshl_add_u64 v[34:35], s[46:47], 0, v[34:35]
	s_mov_b32 s49, s91
	v_lshl_add_u64 v[34:35], v[34:35], 0, s[48:49]
	v_mov_b32_e32 v139, v0
	s_waitcnt lgkmcnt(0)
	s_barrier
	v_lshl_add_u64 v[34:35], v[138:139], 1, v[34:35]
	v_cvt_pk_bf16_f32 v2, v2, v3
	v_cvt_pk_bf16_f32 v3, v4, v5
	v_cvt_pk_bf16_f32 v4, v6, v7
	v_cvt_pk_bf16_f32 v5, v8, v9
	v_cvt_pk_bf16_f32 v6, v10, v11
	v_cvt_pk_bf16_f32 v7, v12, v13
	v_cvt_pk_bf16_f32 v8, v14, v15
	v_cvt_pk_bf16_f32 v9, v16, v17
	v_cvt_pk_bf16_f32 v10, v18, v19
	v_cvt_pk_bf16_f32 v11, v20, v21
	v_cvt_pk_bf16_f32 v12, v22, v23
	v_cvt_pk_bf16_f32 v13, v24, v25
	v_cvt_pk_bf16_f32 v14, v26, v27
	v_cvt_pk_bf16_f32 v15, v28, v29
	v_cvt_pk_bf16_f32 v16, v30, v31
	v_cvt_pk_bf16_f32 v17, v32, v33
	v_permlane32_swap_b32 v2, v4
	v_permlane32_swap_b32 v3, v5
	v_permlane32_swap_b32 v6, v8
	v_permlane32_swap_b32 v7, v9
	v_permlane32_swap_b32 v10, v12
	v_permlane32_swap_b32 v11, v13
	v_permlane32_swap_b32 v14, v16
	v_permlane32_swap_b32 v15, v17
	s_add_i32 s62, s62, s77
	global_store_dwordx4 v[34:35], v[2:5], off
	global_store_dwordx4 v[34:35], v[6:9], off offset:32
	s_cmpk_gt_i32 s62, 0x3ff
	v_readlane_b32 s49, v254, 48
	v_readlane_b32 s50, v254, 49
	v_readlane_b32 s48, v254, 50
	global_store_dwordx4 v[34:35], v[10:13], off offset:64
	global_store_dwordx4 v[34:35], v[14:17], off offset:96
	s_cbranch_scc1 .LBB0_527

;     __host__ __device__ bool next(int i, Unit& u) const {
;         const long L = (long)i * G + c; if (L >= nwg) return false;
;         int wgid = (int)L; { const int q = nwg / NXCD, r = nwg % NXCD, xcd = wgid % NXCD, off = wgid / NXCD; wgid = (xcd < r ? xcd * (q + 1) : r * (q + 1) + (xcd - r) * q) + off; }
;         const int nig = WGM * nN, gid = wgid / nig, fm = gid * WGM, gsz = (nM - fm) < WGM ? (nM - fm) : WGM;
;         u.pm = fm + ((wgid % nig) % gsz); u.pn = (wgid % nig) / gsz; return true;
;     }
; template <class Epi>
; __device__ __forceinline__ void gemm_phase(LAS unsigned char* lds, const Gemm g, const StaticOrder& S, const Epi& E) {
;     ...
;     if constexpr (Epi::USES_RS) { if (E.rs_src()) {
;         const int hi = __builtin_amdgcn_readfirstlane(tid >> 8), rw = tid & 255;
;         Unit u0; (void)S.next(0, u0);
; #pragma unroll
;         for (int j = 0; j < 4; ++j) { Unit uu; const int pmj = S.next(2 * j + hi, uu) ? uu.pm : u0.pm;
;             rsl[(2 * j + hi) * 256 + rw] = rs_from_ssp(E.rs_src(), pmj * 256 + rw); } } }
.LBB0_539:
	v_and_b32_e32 v2, 0xff, v10
	v_lshl_or_b32 v4, s17, 8, v2
	v_ashrrev_i32_e32 v5, 31, v4
	v_lshlrev_b64 v[4:5], 6, v[4:5]
	v_lshl_add_u64 v[8:9], s[12:13], 0, v[4:5]
	global_load_dwordx4 v[44:47], v[8:9], off offset:32
	global_load_dwordx4 v[52:55], v[8:9], off offset:48
	global_load_dwordx4 v[56:59], v[8:9], off
	global_load_dwordx4 v[60:63], v[8:9], off offset:16
	s_add_i32 s21, s20, 2
	v_lshlrev_b32_e32 v1, 2, v2
	s_mul_i32 s16, s21, s77
	s_mul_hi_i32 s17, s21, s77
	s_add_u32 s16, s16, s75
	s_addc_u32 s17, s17, s19
	v_lshl_or_b32 v64, s20, 10, v1
	v_mov_b64_e32 v[4:5], 0x5ff
	v_cmp_gt_i64_e32 vcc, s[16:17], v[4:5]
	s_mov_b32 s17, s18
	s_cbranch_vccnz .LBB0_541
	s_ashr_i32 s17, s16, 31
	s_lshr_b32 s17, s17, 29
	s_add_i32 s17, s16, s17
	s_ashr_i32 s22, s17, 3
	s_and_b32 s17, s17, -8
	s_sub_i32 s16, s16, s17
	s_cmp_lt_i32 s16, 0
	s_movk_i32 s17, 0xc1
	s_cselect_b32 s17, s17, 0xc0
	s_mul_i32 s16, s16, s17
	s_add_i32 s16, s16, s22
	s_mul_hi_i32 s17, s16, 0x2aaaaaab
	s_lshr_b32 s22, s17, 31
	s_ashr_i32 s17, s17, 4
	s_add_i32 s17, s17, s22
	s_lshl_b32 s22, s17, 2
	s_sub_i32 s23, 64, s22
	s_min_i32 s23, s23, 4
	s_abs_i32 s23, s23
	v_cvt_f32_u32_e32 v3, s23
	s_sub_i32 s24, 0, s23
	s_mulk_i32 s17, 0x60
	s_sub_i32 s16, s16, s17
	v_rcp_iflag_f32_e32 v3, v3
	s_ashr_i32 s17, s16, 31
	s_abs_i32 s16, s16
	v_mul_f32_e32 v3, 0x4f7ffffe, v3
	v_cvt_u32_f32_e32 v3, v3
	s_nop 0
	v_readfirstlane_b32 s25, v3
	s_mul_i32 s24, s24, s25
	s_mul_hi_u32 s24, s25, s24
	s_add_i32 s25, s25, s24
	s_mul_hi_u32 s24, s16, s25
	s_mul_i32 s24, s24, s23
	s_sub_i32 s16, s16, s24
	s_sub_i32 s24, s16, s23
	s_cmp_ge_u32 s16, s23
	s_cselect_b32 s16, s24, s16
	s_sub_i32 s24, s16, s23
	s_cmp_ge_u32 s16, s23
	s_cselect_b32 s16, s24, s16
	s_xor_b32 s16, s16, s17
	s_sub_i32 s16, s16, s17
	s_add_i32 s17, s22, s16
.LBB0_541:
	v_lshl_or_b32 v4, s17, 8, v2
	v_ashrrev_i32_e32 v5, 31, v4
	v_lshlrev_b64 v[4:5], 6, v[4:5]
	v_lshl_add_u64 v[8:9], s[12:13], 0, v[4:5]
	global_load_dwordx4 v[84:87], v[8:9], off offset:32
	global_load_dwordx4 v[92:95], v[8:9], off offset:48
	global_load_dwordx4 v[96:99], v[8:9], off
	global_load_dwordx4 v[100:103], v[8:9], off offset:16
	v_lshl_or_b32 v104, s21, 10, v1
	s_add_i32 s21, s20, 4
	s_mul_i32 s16, s21, s77
	s_mul_hi_i32 s17, s21, s77
	s_add_u32 s16, s16, s75
	s_addc_u32 s17, s17, s19
	v_mov_b64_e32 v[4:5], 0x5ff
	v_cmp_gt_i64_e32 vcc, s[16:17], v[4:5]
	s_mov_b32 s17, s18
	s_cbranch_vccnz .LBB0_543
	s_ashr_i32 s17, s16, 31
	s_lshr_b32 s17, s17, 29
	s_add_i32 s17, s16, s17
	s_ashr_i32 s22, s17, 3
	s_and_b32 s17, s17, -8
	s_sub_i32 s16, s16, s17
	s_cmp_lt_i32 s16, 0
	s_movk_i32 s17, 0xc1
	s_cselect_b32 s17, s17, 0xc0
	s_mul_i32 s16, s16, s17
	s_add_i32 s16, s16, s22
	s_mul_hi_i32 s17, s16, 0x2aaaaaab
	s_lshr_b32 s22, s17, 31
	s_ashr_i32 s17, s17, 4
	s_add_i32 s17, s17, s22
	s_lshl_b32 s22, s17, 2
	s_sub_i32 s23, 64, s22
	s_min_i32 s23, s23, 4
	s_abs_i32 s23, s23
	v_cvt_f32_u32_e32 v3, s23
	s_sub_i32 s24, 0, s23
	s_mulk_i32 s17, 0x60
	s_sub_i32 s16, s16, s17
	v_rcp_iflag_f32_e32 v3, v3
	s_ashr_i32 s17, s16, 31
	s_abs_i32 s16, s16
	v_mul_f32_e32 v3, 0x4f7ffffe, v3
	v_cvt_u32_f32_e32 v3, v3
	s_nop 0
	v_readfirstlane_b32 s25, v3
	s_mul_i32 s24, s24, s25
	s_mul_hi_u32 s24, s25, s24
	s_add_i32 s25, s25, s24
	s_mul_hi_u32 s24, s16, s25
	s_mul_i32 s24, s24, s23
	s_sub_i32 s16, s16, s24
	s_sub_i32 s24, s16, s23
	s_cmp_ge_u32 s16, s23
	s_cselect_b32 s16, s24, s16
	s_sub_i32 s24, s16, s23
	s_cmp_ge_u32 s16, s23
	s_cselect_b32 s16, s24, s16
	s_xor_b32 s16, s16, s17
	s_sub_i32 s16, s16, s17
	s_add_i32 s17, s22, s16
;     __host__ __device__ bool next(int i, Unit& u) const {
;         const long L = (long)i * G + c; if (L >= nwg) return false;
;         int wgid = (int)L; { const int q = nwg / NXCD, r = nwg % NXCD, xcd = wgid % NXCD, off = wgid / NXCD; wgid = (xcd < r ? xcd * (q + 1) : r * (q + 1) + (xcd - r) * q) + off; }
;         const int nig = WGM * nN, gid = wgid / nig, fm = gid * WGM, gsz = (nM - fm) < WGM ? (nM - fm) : WGM;
;         u.pm = fm + ((wgid % nig) % gsz); u.pn = (wgid % nig) / gsz; return true;
;     }
; template <class Epi>
; __device__ __forceinline__ void gemm_phase(LAS unsigned char* lds, const Gemm g, const StaticOrder& S, const Epi& E) {
;     ...
;     if constexpr (Epi::USES_RS) { if (E.rs_src()) {
;         const int hi = __builtin_amdgcn_readfirstlane(tid >> 8), rw = tid & 255;
;         Unit u0; (void)S.next(0, u0);
; #pragma unroll
;         for (int j = 0; j < 4; ++j) { Unit uu; const int pmj = S.next(2 * j + hi, uu) ? uu.pm : u0.pm;
;             rsl[(2 * j + hi) * 256 + rw] = rs_from_ssp(E.rs_src(), pmj * 256 + rw); } } }
.LBB0_543:
	v_lshl_or_b32 v4, s17, 8, v2
	v_ashrrev_i32_e32 v5, 31, v4
	v_lshlrev_b64 v[4:5], 6, v[4:5]
	v_lshl_add_u64 v[8:9], s[12:13], 0, v[4:5]
	global_load_dwordx4 v[124:127], v[8:9], off offset:32
	global_load_dwordx4 v[132:135], v[8:9], off offset:48
	global_load_dwordx4 v[136:139], v[8:9], off
	global_load_dwordx4 v[140:143], v[8:9], off offset:16
	s_add_i32 s20, s20, 6
	s_mul_i32 s16, s20, s77
	s_mul_hi_i32 s17, s20, s77
	s_add_u32 s16, s16, s75
	s_addc_u32 s17, s17, s19
	v_lshl_or_b32 v144, s21, 10, v1
	v_mov_b64_e32 v[4:5], 0x5ff
	v_cmp_gt_i64_e32 vcc, s[16:17], v[4:5]
	s_cbranch_vccnz .LBB0_545
	s_ashr_i32 s17, s16, 31
	s_lshr_b32 s17, s17, 29
	s_add_i32 s17, s16, s17
	s_ashr_i32 s18, s17, 3
	s_and_b32 s17, s17, -8
	s_sub_i32 s16, s16, s17
	s_cmp_lt_i32 s16, 0
	s_movk_i32 s17, 0xc1
	s_cselect_b32 s17, s17, 0xc0
	s_mul_i32 s16, s16, s17
	s_add_i32 s16, s16, s18
	s_mul_hi_i32 s17, s16, 0x2aaaaaab
	s_lshr_b32 s18, s17, 31
	s_ashr_i32 s17, s17, 4
	s_add_i32 s17, s17, s18
	s_lshl_b32 s18, s17, 2
	s_sub_i32 s19, 64, s18
	s_min_i32 s19, s19, 4
	s_abs_i32 s19, s19
	v_cvt_f32_u32_e32 v3, s19
	s_sub_i32 s21, 0, s19
	s_mulk_i32 s17, 0x60
	s_sub_i32 s16, s16, s17
	v_rcp_iflag_f32_e32 v3, v3
	s_ashr_i32 s17, s16, 31
	s_abs_i32 s16, s16
	v_mul_f32_e32 v3, 0x4f7ffffe, v3
	v_cvt_u32_f32_e32 v3, v3
	s_nop 0
	v_readfirstlane_b32 s22, v3
	s_mul_i32 s21, s21, s22
	s_mul_hi_u32 s21, s22, s21
	s_add_i32 s22, s22, s21
	s_mul_hi_u32 s21, s16, s22
	s_mul_i32 s21, s21, s19
	s_sub_i32 s16, s16, s21
	s_sub_i32 s21, s16, s19
	s_cmp_ge_u32 s16, s19
	s_cselect_b32 s16, s21, s16
	s_sub_i32 s21, s16, s19
	s_cmp_ge_u32 s16, s19
	s_cselect_b32 s16, s21, s16
	s_xor_b32 s16, s16, s17
	s_sub_i32 s16, s16, s17
	s_add_i32 s18, s18, s16
.LBB0_545:
	v_lshl_or_b32 v2, s18, 8, v2
	v_ashrrev_i32_e32 v3, 31, v2
	v_lshlrev_b64 v[2:3], 6, v[2:3]
	v_lshl_add_u64 v[16:17], s[12:13], 0, v[2:3]
	global_load_dwordx4 v[2:5], v[16:17], off
	global_load_dwordx4 v[6:9], v[16:17], off offset:16
	global_load_dwordx4 v[12:15], v[16:17], off offset:32
	s_nop 0
	global_load_dwordx4 v[16:19], v[16:17], off offset:48
	v_lshl_or_b32 v1, s20, 10, v1
	s_waitcnt vmcnt(4)
	v_pk_add_f32 v[46:47], v[46:47], v[54:55]
	v_pk_add_f32 v[44:45], v[44:45], v[52:53]
	v_pk_add_f32 v[48:49], v[58:59], v[62:63]
	v_pk_add_f32 v[56:57], v[56:57], v[60:61]
	v_pk_add_f32 v[46:47], v[48:49], v[46:47]
	v_pk_add_f32 v[44:45], v[56:57], v[44:45]
	s_nop 0
	v_pk_mov_b32 v[48:49], v[44:45], v[46:47] op_sel:[1,0]
	v_mov_b32_e32 v45, v47
	v_pk_add_f32 v[44:45], v[48:49], v[44:45]
	s_nop 0
	v_add_f32_e32 v43, v44, v45
	v_fmamk_f32 v43, v43, 0x3a800000, v244
	v_rsq_f32_e32 v43, v43
	s_nop 0
	ds_write_b32 v64, v43
	v_pk_add_f32 v[86:87], v[86:87], v[94:95]
	v_pk_add_f32 v[84:85], v[84:85], v[92:93]
	v_pk_add_f32 v[88:89], v[98:99], v[102:103]
	v_pk_add_f32 v[96:97], v[96:97], v[100:101]
	v_pk_add_f32 v[86:87], v[88:89], v[86:87]
	v_pk_add_f32 v[84:85], v[96:97], v[84:85]
	s_nop 0
	v_pk_mov_b32 v[88:89], v[84:85], v[86:87] op_sel:[1,0]
	v_mov_b32_e32 v85, v87
	v_pk_add_f32 v[84:85], v[88:89], v[84:85]
	s_nop 0
	v_add_f32_e32 v83, v84, v85
	v_fmamk_f32 v83, v83, 0x3a800000, v244
	v_rsq_f32_e32 v83, v83
	s_nop 0
	ds_write_b32 v104, v83
	v_pk_add_f32 v[126:127], v[126:127], v[134:135]
	v_pk_add_f32 v[124:125], v[124:125], v[132:133]
	v_pk_add_f32 v[128:129], v[138:139], v[142:143]
	v_pk_add_f32 v[136:137], v[136:137], v[140:141]
	v_pk_add_f32 v[126:127], v[128:129], v[126:127]
	v_pk_add_f32 v[124:125], v[136:137], v[124:125]
	s_nop 0
	v_pk_mov_b32 v[128:129], v[124:125], v[126:127] op_sel:[1,0]
	v_mov_b32_e32 v125, v127
	v_pk_add_f32 v[124:125], v[128:129], v[124:125]
	s_nop 0
	v_add_f32_e32 v123, v124, v125
	v_fmamk_f32 v123, v123, 0x3a800000, v244
	v_rsq_f32_e32 v123, v123
	s_nop 0
	ds_write_b32 v144, v123
	s_waitcnt vmcnt(2)
	v_pk_add_f32 v[4:5], v[4:5], v[8:9]
	v_pk_add_f32 v[2:3], v[2:3], v[6:7]
	s_waitcnt vmcnt(0)
	v_pk_add_f32 v[6:7], v[14:15], v[18:19]
	v_pk_add_f32 v[8:9], v[12:13], v[16:17]
	v_pk_add_f32 v[4:5], v[4:5], v[6:7]
	v_pk_add_f32 v[2:3], v[2:3], v[8:9]
	s_nop 0
	v_pk_mov_b32 v[6:7], v[2:3], v[4:5] op_sel:[1,0]
	v_mov_b32_e32 v3, v5
	v_pk_add_f32 v[2:3], v[6:7], v[2:3]
	s_nop 0
	v_add_f32_e32 v2, v2, v3
	v_fmamk_f32 v2, v2, 0x3a800000, v244
	v_rsq_f32_e32 v2, v2
	ds_write_b32 v1, v2

; #define GAS __attribute__((address_space(1)))
; __device__ __forceinline__ float rs_from_ssp(const GAS float* ssp, int row) {
;     const GAS f32x4* p = (const GAS f32x4*)(ssp + (size_t)row * 16);
;     const f32x4 a = p[0], b = p[1], c = p[2], d = p[3];
;     const f32x4 s = (a + b) + (c + d);
;     return __builtin_amdgcn_rsqf(((s.x + s.y) + (s.z + s.w)) * (1.f / 1024.f) + EPS);
; }
; template <class Epi>
; __device__ __forceinline__ void gemm_phase(LAS unsigned char* lds, const Gemm g, const StaticOrder& S, const Epi& E) {
;     ...
;     if constexpr (Epi::USES_RS) { if (E.rs_src()) {
;         const int hi = __builtin_amdgcn_readfirstlane(tid >> 8), rw = tid & 255;
;         Unit u0; (void)S.next(0, u0);
; #pragma unroll
;         for (int j = 0; j < 4; ++j) { Unit uu; const int pmj = S.next(2 * j + hi, uu) ? uu.pm : u0.pm;
;             rsl[(2 * j + hi) * 256 + rw] = rs_from_ssp(E.rs_src(), pmj * 256 + rw); } } }
.LBB0_671:
	s_waitcnt lgkmcnt(0)
	v_and_b32_e32 v3, 0xff, v1
	v_lshl_or_b32 v4, s9, 8, v3
	v_ashrrev_i32_e32 v5, 31, v4
	v_lshlrev_b64 v[4:5], 6, v[4:5]
	v_lshl_add_u64 v[16:17], s[12:13], 0, v[4:5]
	global_load_dwordx4 v[44:47], v[16:17], off offset:32
	global_load_dwordx4 v[48:51], v[16:17], off offset:48
	global_load_dwordx4 v[52:55], v[16:17], off
	s_nop 0
	global_load_dwordx4 v[56:59], v[16:17], off offset:16
	s_add_i32 s15, s14, 2
	s_mul_i32 s8, s15, s77
	s_mul_hi_i32 s9, s15, s77
	s_add_u32 s8, s8, s75
	s_addc_u32 s9, s9, s11
	v_lshlrev_b32_e32 v2, 2, v3
	v_cmp_gt_i64_e32 vcc, s[8:9], v[178:179]
	s_and_b64 vcc, exec, vcc
	s_mov_b32 s9, s10
	v_lshl_or_b32 v64, s14, 10, v2
	s_cbranch_vccnz .LBB0_677
	s_ashr_i32 s9, s8, 31
	s_lshr_b32 s9, s9, 29
	s_add_i32 s16, s8, s9
	s_and_b32 s9, s16, -8
	s_sub_i32 s17, s8, s9
	s_cmp_lt_i32 s17, 0
	s_mov_b64 s[8:9], -1
	s_cbranch_scc1 .LBB0_674
	s_lshl_b32 s18, s17, 7
	s_mov_b64 s[8:9], 0

; #define GAS __attribute__((address_space(1)))
; __device__ __forceinline__ float rs_from_ssp(const GAS float* ssp, int row) {
;     const GAS f32x4* p = (const GAS f32x4*)(ssp + (size_t)row * 16);
;     const f32x4 a = p[0], b = p[1], c = p[2], d = p[3];
;     const f32x4 s = (a + b) + (c + d);
;     return __builtin_amdgcn_rsqf(((s.x + s.y) + (s.z + s.w)) * (1.f / 1024.f) + EPS);
; }
; template <class Epi>
; __device__ __forceinline__ void gemm_phase(LAS unsigned char* lds, const Gemm g, const StaticOrder& S, const Epi& E) {
;     ...
;     if constexpr (Epi::USES_RS) { if (E.rs_src()) {
;         const int hi = __builtin_amdgcn_readfirstlane(tid >> 8), rw = tid & 255;
;         Unit u0; (void)S.next(0, u0);
; #pragma unroll
;         for (int j = 0; j < 4; ++j) { Unit uu; const int pmj = S.next(2 * j + hi, uu) ? uu.pm : u0.pm;
;             rsl[(2 * j + hi) * 256 + rw] = rs_from_ssp(E.rs_src(), pmj * 256 + rw); } } }
.LBB0_677:
	v_lshl_or_b32 v4, s9, 8, v3
	v_ashrrev_i32_e32 v5, 31, v4
	v_lshlrev_b64 v[4:5], 6, v[4:5]
	v_lshl_add_u64 v[16:17], s[12:13], 0, v[4:5]
	global_load_dwordx4 v[84:87], v[16:17], off offset:32
	global_load_dwordx4 v[88:91], v[16:17], off offset:48
	global_load_dwordx4 v[92:95], v[16:17], off
	s_nop 0
	global_load_dwordx4 v[96:99], v[16:17], off offset:16
	v_lshl_or_b32 v104, s15, 10, v2
	s_add_i32 s15, s14, 4
	s_mul_i32 s8, s15, s77
	s_mul_hi_i32 s9, s15, s77
	s_add_u32 s8, s8, s75
	s_addc_u32 s9, s9, s11
	v_cmp_gt_i64_e32 vcc, s[8:9], v[178:179]
	s_mov_b32 s9, s10
	s_cbranch_vccnz .LBB0_683
	s_ashr_i32 s9, s8, 31
	s_lshr_b32 s9, s9, 29
	s_add_i32 s16, s8, s9
	s_and_b32 s9, s16, -8
	s_sub_i32 s17, s8, s9
	s_cmp_lt_i32 s17, 0
	s_mov_b64 s[8:9], -1
	s_cbranch_scc1 .LBB0_680
	s_lshl_b32 s18, s17, 7
	s_mov_b64 s[8:9], 0

; #define GAS __attribute__((address_space(1)))
; __device__ __forceinline__ float rs_from_ssp(const GAS float* ssp, int row) {
;     const GAS f32x4* p = (const GAS f32x4*)(ssp + (size_t)row * 16);
;     const f32x4 a = p[0], b = p[1], c = p[2], d = p[3];
;     const f32x4 s = (a + b) + (c + d);
;     return __builtin_amdgcn_rsqf(((s.x + s.y) + (s.z + s.w)) * (1.f / 1024.f) + EPS);
; }
; template <class Epi>
; __device__ __forceinline__ void gemm_phase(LAS unsigned char* lds, const Gemm g, const StaticOrder& S, const Epi& E) {
;     ...
;     if constexpr (Epi::USES_RS) { if (E.rs_src()) {
;         const int hi = __builtin_amdgcn_readfirstlane(tid >> 8), rw = tid & 255;
;         Unit u0; (void)S.next(0, u0);
; #pragma unroll
;         for (int j = 0; j < 4; ++j) { Unit uu; const int pmj = S.next(2 * j + hi, uu) ? uu.pm : u0.pm;
;             rsl[(2 * j + hi) * 256 + rw] = rs_from_ssp(E.rs_src(), pmj * 256 + rw); } } }
.LBB0_683:
	v_lshl_or_b32 v4, s9, 8, v3
	v_ashrrev_i32_e32 v5, 31, v4
	v_lshlrev_b64 v[4:5], 6, v[4:5]
	v_lshl_add_u64 v[16:17], s[12:13], 0, v[4:5]
	global_load_dwordx4 v[124:127], v[16:17], off offset:32
	global_load_dwordx4 v[128:131], v[16:17], off offset:48
	global_load_dwordx4 v[132:135], v[16:17], off
	s_nop 0
	global_load_dwordx4 v[136:139], v[16:17], off offset:16
	s_add_i32 s14, s14, 6
	s_mul_i32 s8, s14, s77
	s_mul_hi_i32 s9, s14, s77
	s_add_u32 s8, s8, s75
	s_addc_u32 s9, s9, s11
	v_cmp_gt_i64_e32 vcc, s[8:9], v[178:179]
	s_and_b64 vcc, exec, vcc
	v_lshl_or_b32 v144, s15, 10, v2
	s_cbranch_vccnz .LBB0_689
	s_ashr_i32 s9, s8, 31
	s_lshr_b32 s9, s9, 29
	s_add_i32 s10, s8, s9
	s_and_b32 s9, s10, -8
	s_sub_i32 s11, s8, s9
	s_cmp_lt_i32 s11, 0
	s_mov_b64 s[8:9], -1
	s_cbranch_scc1 .LBB0_686
	s_lshl_b32 s15, s11, 7
	s_mov_b64 s[8:9], 0

; #define GAS __attribute__((address_space(1)))
; __device__ __forceinline__ float rs_from_ssp(const GAS float* ssp, int row) {
;     const GAS f32x4* p = (const GAS f32x4*)(ssp + (size_t)row * 16);
;     const f32x4 a = p[0], b = p[1], c = p[2], d = p[3];
;     const f32x4 s = (a + b) + (c + d);
;     return __builtin_amdgcn_rsqf(((s.x + s.y) + (s.z + s.w)) * (1.f / 1024.f) + EPS);
; }
; template <class Epi>
; __device__ __forceinline__ void gemm_phase(LAS unsigned char* lds, const Gemm g, const StaticOrder& S, const Epi& E) {
;     ...
;     if constexpr (Epi::USES_RS) { if (E.rs_src()) {
;         const int hi = __builtin_amdgcn_readfirstlane(tid >> 8), rw = tid & 255;
;         Unit u0; (void)S.next(0, u0);
; #pragma unroll
;         for (int j = 0; j < 4; ++j) { Unit uu; const int pmj = S.next(2 * j + hi, uu) ? uu.pm : u0.pm;
;             rsl[(2 * j + hi) * 256 + rw] = rs_from_ssp(E.rs_src(), pmj * 256 + rw); } } }
.LBB0_689:
	v_lshl_or_b32 v4, s10, 8, v3
	v_ashrrev_i32_e32 v5, 31, v4
	v_lshlrev_b64 v[4:5], 6, v[4:5]
	v_lshl_add_u64 v[16:17], s[12:13], 0, v[4:5]
	global_load_dwordx4 v[4:7], v[16:17], off
	global_load_dwordx4 v[8:11], v[16:17], off offset:16
	global_load_dwordx4 v[12:15], v[16:17], off offset:32
	s_nop 0
	global_load_dwordx4 v[16:19], v[16:17], off offset:48
	v_lshl_or_b32 v2, s14, 10, v2
	s_waitcnt vmcnt(4)
	v_pk_add_f32 v[46:47], v[46:47], v[50:51]
	v_pk_add_f32 v[44:45], v[44:45], v[48:49]
	v_pk_add_f32 v[54:55], v[54:55], v[58:59]
	v_pk_add_f32 v[52:53], v[52:53], v[56:57]
	v_pk_add_f32 v[46:47], v[54:55], v[46:47]
	v_pk_add_f32 v[44:45], v[52:53], v[44:45]
	s_nop 0
	v_pk_mov_b32 v[48:49], v[44:45], v[46:47] op_sel:[1,0]
	v_mov_b32_e32 v45, v47
	v_pk_add_f32 v[44:45], v[48:49], v[44:45]
	s_nop 0
	v_add_f32_e32 v44, v44, v45
	v_fmamk_f32 v44, v44, 0x3a800000, v244
	v_rsq_f32_e32 v44, v44
	s_nop 0
	ds_write_b32 v64, v44
	v_pk_add_f32 v[86:87], v[86:87], v[90:91]
	v_pk_add_f32 v[84:85], v[84:85], v[88:89]
	v_pk_add_f32 v[94:95], v[94:95], v[98:99]
	v_pk_add_f32 v[92:93], v[92:93], v[96:97]
	v_pk_add_f32 v[86:87], v[94:95], v[86:87]
	v_pk_add_f32 v[84:85], v[92:93], v[84:85]
	s_nop 0
	v_pk_mov_b32 v[88:89], v[84:85], v[86:87] op_sel:[1,0]
	v_mov_b32_e32 v85, v87
	v_pk_add_f32 v[84:85], v[88:89], v[84:85]
	s_nop 0
	v_add_f32_e32 v84, v84, v85
	v_fmamk_f32 v84, v84, 0x3a800000, v244
	v_rsq_f32_e32 v84, v84
	s_nop 0
	ds_write_b32 v104, v84
	v_pk_add_f32 v[126:127], v[126:127], v[130:131]
	v_pk_add_f32 v[124:125], v[124:125], v[128:129]
	v_pk_add_f32 v[134:135], v[134:135], v[138:139]
	v_pk_add_f32 v[132:133], v[132:133], v[136:137]
	v_pk_add_f32 v[126:127], v[134:135], v[126:127]
	v_pk_add_f32 v[124:125], v[132:133], v[124:125]
	s_nop 0
	v_pk_mov_b32 v[128:129], v[124:125], v[126:127] op_sel:[1,0]
	v_mov_b32_e32 v125, v127
	v_pk_add_f32 v[124:125], v[128:129], v[124:125]
	s_nop 0
	v_add_f32_e32 v124, v124, v125
	v_fmamk_f32 v124, v124, 0x3a800000, v244
	v_rsq_f32_e32 v124, v124
	s_nop 0
	ds_write_b32 v144, v124
	s_waitcnt vmcnt(2)
	v_pk_add_f32 v[6:7], v[6:7], v[10:11]
	v_pk_add_f32 v[4:5], v[4:5], v[8:9]
	s_waitcnt vmcnt(0)
	v_pk_add_f32 v[8:9], v[14:15], v[18:19]
	v_pk_add_f32 v[10:11], v[12:13], v[16:17]
	v_pk_add_f32 v[6:7], v[6:7], v[8:9]
	v_pk_add_f32 v[4:5], v[4:5], v[10:11]
	s_nop 0
	v_pk_mov_b32 v[8:9], v[4:5], v[6:7] op_sel:[1,0]
	v_mov_b32_e32 v5, v7
	v_pk_add_f32 v[4:5], v[8:9], v[4:5]
	s_nop 0
	v_add_f32_e32 v3, v4, v5
	v_fmamk_f32 v3, v3, 0x3a800000, v244
	v_rsq_f32_e32 v3, v3
	ds_write_b32 v2, v3

;     __host__ __device__ bool next(int i, Unit& u) const {
;         const long L = (long)i * G + c; if (L >= nwg) return false;
;         int wgid = (int)L; { const int q = nwg / NXCD, r = nwg % NXCD, xcd = wgid % NXCD, off = wgid / NXCD; wgid = (xcd < r ? xcd * (q + 1) : r * (q + 1) + (xcd - r) * q) + off; }
;         const int nig = WGM * nN, gid = wgid / nig, fm = gid * WGM, gsz = (nM - fm) < WGM ? (nM - fm) : WGM;
;         u.pm = fm + ((wgid % nig) % gsz); u.pn = (wgid % nig) / gsz; return true;
;     }
; template <class Epi>
; __device__ __forceinline__ void gemm_phase(LAS unsigned char* lds, const Gemm g, const StaticOrder& S, const Epi& E) {
;     ...
;     if constexpr (Epi::USES_RS) { if (E.rs_src()) {
;         const int hi = __builtin_amdgcn_readfirstlane(tid >> 8), rw = tid & 255;
;         Unit u0; (void)S.next(0, u0);
; #pragma unroll
;         for (int j = 0; j < 4; ++j) { Unit uu; const int pmj = S.next(2 * j + hi, uu) ? uu.pm : u0.pm;
;             rsl[(2 * j + hi) * 256 + rw] = rs_from_ssp(E.rs_src(), pmj * 256 + rw); } } }
.LBB0_757:
	v_and_b32_e32 v1, 0xff, v2
	v_lshl_or_b32 v4, s7, 8, v1
	v_ashrrev_i32_e32 v5, 31, v4
	v_lshlrev_b64 v[4:5], 6, v[4:5]
	v_lshl_add_u64 v[16:17], s[12:13], 0, v[4:5]
	global_load_dwordx4 v[44:47], v[16:17], off
	global_load_dwordx4 v[48:51], v[16:17], off offset:16
	global_load_dwordx4 v[52:55], v[16:17], off offset:32
	s_nop 0
	global_load_dwordx4 v[56:59], v[16:17], off offset:48
	s_add_i32 s15, s14, 2
	s_mul_i32 s6, s15, s77
	s_mul_hi_i32 s7, s15, s77
	s_add_u32 s6, s6, s75
	s_addc_u32 s7, s7, s11
	v_lshlrev_b32_e32 v3, 2, v1
	s_mov_b32 s16, s10
	v_lshl_or_b32 v64, s14, 10, v3
	v_mov_b64_e32 v[6:7], 0x2ff
	s_cbranch_vccnz .LBB0_759
	s_ashr_i32 s7, s6, 31
	s_lshr_b32 s7, s7, 29
	s_add_i32 s7, s6, s7
	s_ashr_i32 s16, s7, 3
	s_and_b32 s7, s7, -8
	s_sub_i32 s6, s6, s7
	s_cmp_lt_i32 s6, 0
	s_movk_i32 s7, 0x61
	s_cselect_b32 s7, s7, 0x60
	s_mul_i32 s6, s6, s7
	s_add_i32 s6, s6, s16
	s_mul_hi_i32 s7, s6, 0x2aaaaaab
	s_lshr_b32 s16, s7, 31
	s_ashr_i32 s7, s7, 3
	s_add_i32 s7, s7, s16
	s_lshl_b32 s16, s7, 2
	s_sub_i32 s17, 64, s16
	s_min_i32 s17, s17, 4
	s_abs_i32 s17, s17
	v_cvt_f32_u32_e32 v4, s17
	s_sub_i32 s19, 0, s17
	s_mul_i32 s7, s7, 48
	s_sub_i32 s6, s6, s7
	v_rcp_iflag_f32_e32 v4, v4
	s_ashr_i32 s7, s6, 31
	s_abs_i32 s6, s6
	v_mul_f32_e32 v4, 0x4f7ffffe, v4
	v_cvt_u32_f32_e32 v4, v4
	s_nop 0
	v_readfirstlane_b32 s20, v4
	s_mul_i32 s19, s19, s20
	s_mul_hi_u32 s19, s20, s19
	s_add_i32 s20, s20, s19
	s_mul_hi_u32 s19, s6, s20
	s_mul_i32 s19, s19, s17
	s_sub_i32 s6, s6, s19
	s_sub_i32 s19, s6, s17
	s_cmp_ge_u32 s6, s17
	s_cselect_b32 s6, s19, s6
	s_sub_i32 s19, s6, s17
	s_cmp_ge_u32 s6, s17
	s_cselect_b32 s6, s19, s6
	s_xor_b32 s6, s6, s7
	s_sub_i32 s6, s6, s7
	s_add_i32 s16, s16, s6
.LBB0_759:
	v_lshl_or_b32 v4, s16, 8, v1
	v_ashrrev_i32_e32 v5, 31, v4
	v_lshlrev_b64 v[4:5], 6, v[4:5]
	v_lshl_add_u64 v[16:17], s[12:13], 0, v[4:5]
	global_load_dwordx4 v[84:87], v[16:17], off
	global_load_dwordx4 v[88:91], v[16:17], off offset:16
	global_load_dwordx4 v[92:95], v[16:17], off offset:32
	s_nop 0
	global_load_dwordx4 v[96:99], v[16:17], off offset:48
	v_lshl_or_b32 v104, s15, 10, v3
	s_add_i32 s15, s14, 4
	s_mul_i32 s6, s15, s77
	s_mul_hi_i32 s7, s15, s77
	s_add_u32 s6, s6, s75
	s_addc_u32 s7, s7, s11
	s_mov_b32 s16, s10
	v_mov_b64_e32 v[6:7], 0x2ff
	s_cbranch_vccnz .LBB0_761
	s_ashr_i32 s7, s6, 31
	s_lshr_b32 s7, s7, 29
	s_add_i32 s7, s6, s7
	s_ashr_i32 s16, s7, 3
	s_and_b32 s7, s7, -8
	s_sub_i32 s6, s6, s7
	s_cmp_lt_i32 s6, 0
	s_movk_i32 s7, 0x61
	s_cselect_b32 s7, s7, 0x60
	s_mul_i32 s6, s6, s7
	s_add_i32 s6, s6, s16
	s_mul_hi_i32 s7, s6, 0x2aaaaaab
	s_lshr_b32 s16, s7, 31
	s_ashr_i32 s7, s7, 3
	s_add_i32 s7, s7, s16
	s_lshl_b32 s16, s7, 2
	s_sub_i32 s17, 64, s16
	s_min_i32 s17, s17, 4
	s_abs_i32 s17, s17
	v_cvt_f32_u32_e32 v4, s17
	s_sub_i32 s19, 0, s17
	s_mul_i32 s7, s7, 48
	s_sub_i32 s6, s6, s7
	v_rcp_iflag_f32_e32 v4, v4
	s_ashr_i32 s7, s6, 31
	s_abs_i32 s6, s6
	v_mul_f32_e32 v4, 0x4f7ffffe, v4
	v_cvt_u32_f32_e32 v4, v4
	s_nop 0
	v_readfirstlane_b32 s20, v4
	s_mul_i32 s19, s19, s20
	s_mul_hi_u32 s19, s20, s19
	s_add_i32 s20, s20, s19
	s_mul_hi_u32 s19, s6, s20
	s_mul_i32 s19, s19, s17
	s_sub_i32 s6, s6, s19
	s_sub_i32 s19, s6, s17
	s_cmp_ge_u32 s6, s17
	s_cselect_b32 s6, s19, s6
	s_sub_i32 s19, s6, s17
	s_cmp_ge_u32 s6, s17
	s_cselect_b32 s6, s19, s6
	s_xor_b32 s6, s6, s7
	s_sub_i32 s6, s6, s7
	s_add_i32 s16, s16, s6
;     __host__ __device__ bool next(int i, Unit& u) const {
;         const long L = (long)i * G + c; if (L >= nwg) return false;
;         int wgid = (int)L; { const int q = nwg / NXCD, r = nwg % NXCD, xcd = wgid % NXCD, off = wgid / NXCD; wgid = (xcd < r ? xcd * (q + 1) : r * (q + 1) + (xcd - r) * q) + off; }
;         const int nig = WGM * nN, gid = wgid / nig, fm = gid * WGM, gsz = (nM - fm) < WGM ? (nM - fm) : WGM;
;         u.pm = fm + ((wgid % nig) % gsz); u.pn = (wgid % nig) / gsz; return true;
;     }
; template <class Epi>
; __device__ __forceinline__ void gemm_phase(LAS unsigned char* lds, const Gemm g, const StaticOrder& S, const Epi& E) {
;     ...
;     if constexpr (Epi::USES_RS) { if (E.rs_src()) {
;         const int hi = __builtin_amdgcn_readfirstlane(tid >> 8), rw = tid & 255;
;         Unit u0; (void)S.next(0, u0);
; #pragma unroll
;         for (int j = 0; j < 4; ++j) { Unit uu; const int pmj = S.next(2 * j + hi, uu) ? uu.pm : u0.pm;
;             rsl[(2 * j + hi) * 256 + rw] = rs_from_ssp(E.rs_src(), pmj * 256 + rw); } } }
.LBB0_761:
	v_lshl_or_b32 v4, s16, 8, v1
	v_ashrrev_i32_e32 v5, 31, v4
	v_lshlrev_b64 v[4:5], 6, v[4:5]
	v_lshl_add_u64 v[16:17], s[12:13], 0, v[4:5]
	global_load_dwordx4 v[124:127], v[16:17], off
	global_load_dwordx4 v[128:131], v[16:17], off offset:16
	global_load_dwordx4 v[132:135], v[16:17], off offset:32
	s_nop 0
	global_load_dwordx4 v[136:139], v[16:17], off offset:48
	s_add_i32 s14, s14, 6
	s_mul_i32 s6, s14, s77
	s_mul_hi_i32 s7, s14, s77
	s_add_u32 s6, s6, s75
	s_addc_u32 s7, s7, s11
	v_lshl_or_b32 v144, s15, 10, v3
	v_mov_b64_e32 v[6:7], 0x2ff
	s_cbranch_vccnz .LBB0_763
	s_ashr_i32 s7, s6, 31
	s_lshr_b32 s7, s7, 29
	s_add_i32 s7, s6, s7
	s_ashr_i32 s10, s7, 3
	s_and_b32 s7, s7, -8
	s_sub_i32 s6, s6, s7
	s_cmp_lt_i32 s6, 0
	s_movk_i32 s7, 0x61
	s_cselect_b32 s7, s7, 0x60
	s_mul_i32 s6, s6, s7
	s_add_i32 s6, s6, s10
	s_mul_hi_i32 s7, s6, 0x2aaaaaab
	s_lshr_b32 s10, s7, 31
	s_ashr_i32 s7, s7, 3
	s_add_i32 s7, s7, s10
	s_lshl_b32 s10, s7, 2
	s_sub_i32 s11, 64, s10
	s_min_i32 s11, s11, 4
	s_abs_i32 s11, s11
	v_cvt_f32_u32_e32 v4, s11
	s_sub_i32 s15, 0, s11
	s_mul_i32 s7, s7, 48
	s_sub_i32 s6, s6, s7
	v_rcp_iflag_f32_e32 v4, v4
	s_ashr_i32 s7, s6, 31
	s_abs_i32 s6, s6
	v_mul_f32_e32 v4, 0x4f7ffffe, v4
	v_cvt_u32_f32_e32 v4, v4
	s_nop 0
	v_readfirstlane_b32 s16, v4
	s_mul_i32 s15, s15, s16
	s_mul_hi_u32 s15, s16, s15
	s_add_i32 s16, s16, s15
	s_mul_hi_u32 s15, s6, s16
	s_mul_i32 s15, s15, s11
	s_sub_i32 s6, s6, s15
	s_sub_i32 s15, s6, s11
	s_cmp_ge_u32 s6, s11
	s_cselect_b32 s6, s15, s6
	s_sub_i32 s15, s6, s11
	s_cmp_ge_u32 s6, s11
	s_cselect_b32 s6, s15, s6
	s_xor_b32 s6, s6, s7
	s_sub_i32 s6, s6, s7
	s_add_i32 s10, s10, s6
.LBB0_763:
	v_lshl_or_b32 v4, s10, 8, v1
	v_ashrrev_i32_e32 v5, 31, v4
	v_lshlrev_b64 v[4:5], 6, v[4:5]
	v_lshl_add_u64 v[16:17], s[12:13], 0, v[4:5]
	global_load_dwordx4 v[4:7], v[16:17], off
	global_load_dwordx4 v[8:11], v[16:17], off offset:16
	global_load_dwordx4 v[12:15], v[16:17], off offset:32
	s_nop 0
	global_load_dwordx4 v[16:19], v[16:17], off offset:48
	v_lshl_or_b32 v3, s14, 10, v3
	s_waitcnt vmcnt(4)
	v_pk_add_f32 v[46:47], v[46:47], v[50:51]
	v_pk_add_f32 v[44:45], v[44:45], v[48:49]
	v_pk_add_f32 v[48:49], v[54:55], v[58:59]
	v_pk_add_f32 v[50:51], v[52:53], v[56:57]
	v_pk_add_f32 v[46:47], v[46:47], v[48:49]
	v_pk_add_f32 v[44:45], v[44:45], v[50:51]
	s_nop 0
	v_pk_mov_b32 v[48:49], v[44:45], v[46:47] op_sel:[1,0]
	v_mov_b32_e32 v45, v47
	v_pk_add_f32 v[44:45], v[48:49], v[44:45]
	v_add_f32_e32 v44, v44, v45
	v_fmamk_f32 v44, v44, 0x3a800000, v244
	v_rsq_f32_e32 v44, v44
	v_cmp_gt_i64_e32 vcc, s[6:7], v[46:47]
	s_nop 0
	ds_write_b32 v64, v44
	v_pk_add_f32 v[86:87], v[86:87], v[90:91]
	v_pk_add_f32 v[84:85], v[84:85], v[88:89]
	v_pk_add_f32 v[88:89], v[94:95], v[98:99]
	v_pk_add_f32 v[90:91], v[92:93], v[96:97]
	v_pk_add_f32 v[86:87], v[86:87], v[88:89]
	v_pk_add_f32 v[84:85], v[84:85], v[90:91]
	s_nop 0
	v_pk_mov_b32 v[88:89], v[84:85], v[86:87] op_sel:[1,0]
	v_mov_b32_e32 v85, v87
	v_pk_add_f32 v[84:85], v[88:89], v[84:85]
	v_add_f32_e32 v84, v84, v85
	v_fmamk_f32 v84, v84, 0x3a800000, v244
	v_rsq_f32_e32 v84, v84
	v_cmp_gt_i64_e32 vcc, s[6:7], v[86:87]
	s_nop 0
	ds_write_b32 v104, v84
	v_pk_add_f32 v[126:127], v[126:127], v[130:131]
	v_pk_add_f32 v[124:125], v[124:125], v[128:129]
	v_pk_add_f32 v[128:129], v[134:135], v[138:139]
	v_pk_add_f32 v[130:131], v[132:133], v[136:137]
	v_pk_add_f32 v[126:127], v[126:127], v[128:129]
	v_pk_add_f32 v[124:125], v[124:125], v[130:131]
	s_nop 0
	v_pk_mov_b32 v[128:129], v[124:125], v[126:127] op_sel:[1,0]
	v_mov_b32_e32 v125, v127
	v_pk_add_f32 v[124:125], v[128:129], v[124:125]
	v_add_f32_e32 v124, v124, v125
	v_fmamk_f32 v124, v124, 0x3a800000, v244
	v_rsq_f32_e32 v124, v124
	v_cmp_gt_i64_e32 vcc, s[6:7], v[126:127]
	s_nop 0
	ds_write_b32 v144, v124
	s_waitcnt vmcnt(2)
	v_pk_add_f32 v[6:7], v[6:7], v[10:11]
	v_pk_add_f32 v[4:5], v[4:5], v[8:9]
	s_waitcnt vmcnt(0)
	v_pk_add_f32 v[8:9], v[14:15], v[18:19]
	v_pk_add_f32 v[10:11], v[12:13], v[16:17]
	v_pk_add_f32 v[6:7], v[6:7], v[8:9]
	v_pk_add_f32 v[4:5], v[4:5], v[10:11]
	s_nop 0
	v_pk_mov_b32 v[8:9], v[4:5], v[6:7] op_sel:[1,0]
	v_mov_b32_e32 v5, v7
	v_pk_add_f32 v[4:5], v[8:9], v[4:5]
	s_nop 0
	v_add_f32_e32 v1, v4, v5
	v_fmamk_f32 v1, v1, 0x3a800000, v244
	v_rsq_f32_e32 v1, v1
	ds_write_b32 v3, v1
